# grid barrier: XCD leaders issue their first poll of the arrival counter together with their arrival atomic (no second round trip when they are already released)
# baseline (speedup 1.0000x reference)
; __device__ __forceinline__ unsigned xb_ld(unsigned* p)              { return __hip_atomic_load(p, __ATOMIC_RELAXED, __HIP_MEMORY_SCOPE_AGENT); }
; __device__ __forceinline__ unsigned xb_add(unsigned* p, unsigned v) { return __hip_atomic_fetch_add(p, v, __ATOMIC_RELAXED, __HIP_MEMORY_SCOPE_AGENT); }
; #define XB_SPIN(cond, bar) do { unsigned _sp = 0; while (cond) { __builtin_amdgcn_s_sleep(1); \
;     if ((++_sp & 255u) == 0u) { if (xb_ld(&(bar)[XB_TMO])) break; if (_sp > XB_SPIN_CAP) { atomicAdd(&(bar)[XB_TMO], 1u); break; } } } } while (0)
; __device__ __forceinline__ void xcd_barrier(const XcdBarrier& b) {
;     ...
;             const unsigned og = xb_add(&bar[XB_TOP], 1u);
;             const unsigned tg = og / nx;
;             if (og + 1u == (tg + 1u) * nx) xb_add(&bar[XB_TOPGEN], 1u);
;             else XB_SPIN(xb_ld(&bar[XB_TOPGEN]) == tg, bar);
.LBB0_1843:
	s_mov_b64 s[2:3], exec
	buffer_wbl2 sc1
	s_waitcnt lgkmcnt(0)
	s_waitcnt vmcnt(0)
	v_mbcnt_lo_u32_b32 v1, s2, 0
	v_mbcnt_hi_u32_b32 v1, s3, v1
	v_cmp_eq_u32_e32 vcc, 0, v1
	s_and_saveexec_b64 s[18:19], vcc
	s_cbranch_execz .LBB0_1845
	s_bcnt1_i32_b64 s2, s[2:3]
	v_mov_b32_e32 v2, s2
	v_readlane_b32 s2, v251, 27
	v_readlane_b32 s3, v251, 28
	s_nop 4
	global_atomic_add v2, v197, v2, s[2:3] sc0
	global_load_dword v6, v197, s[2:3] sc1
.LBB0_1845:
	s_or_b64 exec, exec, s[18:19]
	s_waitcnt vmcnt(0)
	v_readfirstlane_b32 s2, v2
	v_cvt_f32_u32_e32 v2, v0
	v_sub_u32_e32 v3, 0, v0
	v_add_u32_e32 v1, s2, v1
	v_readlane_b32 s2, v251, 29
	v_rcp_iflag_f32_e32 v2, v2
	v_readlane_b32 s3, v251, 30
	s_mov_b64 s[18:19], 0
	v_mul_f32_e32 v2, 0x4f7ffffe, v2
	v_cvt_u32_f32_e32 v2, v2
	v_mul_lo_u32 v3, v3, v2
	v_mul_hi_u32 v3, v2, v3
	v_add_u32_e32 v2, v2, v3
	v_mul_hi_u32 v2, v1, v2
	v_mul_lo_u32 v3, v2, v0
	v_sub_u32_e32 v3, v1, v3
	v_cmp_ge_u32_e32 vcc, v3, v0
	v_add_u32_e32 v4, 1, v2
	v_add_u32_e32 v1, 1, v1
	v_cndmask_b32_e32 v2, v2, v4, vcc
	v_sub_u32_e32 v4, v3, v0
	v_cndmask_b32_e32 v3, v3, v4, vcc
	v_cmp_ge_u32_e32 vcc, v3, v0
	v_add_u32_e32 v3, 1, v2
	s_nop 0
	v_cndmask_b32_e32 v2, v2, v3, vcc
	v_mul_lo_u32 v3, v0, v2
	v_add_u32_e32 v0, v3, v0
	v_mov_b32_e32 v5, v0
	v_cmp_ne_u32_e32 vcc, v1, v0
	v_mov_b64_e32 v[0:1], s[2:3]
	s_and_saveexec_b64 s[2:3], vcc
	s_cbranch_execz .LBB0_1857
	s_mov_b64 s[24:25], 0
	v_cmp_gt_u32_e32 vcc, v5, v6
	s_and_saveexec_b64 s[18:19], vcc
	s_cbranch_execz .LBB0_1856
	s_mov_b32 s21, 1
	s_branch .LBB0_1849
